# GEMM k-loops: s_setprio 1 issued before the pre-MFMA barrier and s_setprio 0 after the post-MFMA barrier (the MFMA block is the only thing between the two barriers)
# baseline (speedup 1.0000x reference)
.LBB0_259:
	ds_read_b128 v[152:155], v149
	ds_read_b128 v[156:159], v149 offset:1024
	ds_read_b128 v[160:163], v149 offset:2048
	ds_read_b128 v[164:167], v149 offset:3072
	ds_read_b128 v[168:171], v150
	ds_read_b128 v[172:175], v150 offset:1024
	ds_read_b128 v[176:179], v150 offset:2048
	ds_read_b128 v[184:187], v150 offset:3072
	s_add_u32 s24, s22, 0xfffc0080
	s_addc_u32 s25, s23, -1
	s_cmp_eq_u32 s51, 12
	s_cselect_b32 s27, s15, s25
	s_cselect_b32 s26, s47, s24
	s_cselect_b32 s25, s13, s50
	s_cselect_b32 s24, s48, s49
	v_lshl_add_u64 v[144:145], s[22:23], 0, v[136:137]
	s_add_i32 m0, s21, 0xc000
	ds_read_b128 v[188:191], v151
	ds_read_b128 v[192:195], v151 offset:1024
	ds_read_b128 v[196:199], v151 offset:2048
	ds_read_b128 v[200:203], v151 offset:3072
	ds_read_b128 v[204:207], v151 offset:4096
	ds_read_b128 v[208:211], v151 offset:5120
	ds_read_b128 v[212:215], v151 offset:6144
	ds_read_b128 v[216:219], v151 offset:7168
	global_load_lds_dwordx4 v[144:145], off
	v_lshl_add_u64 v[144:145], s[22:23], 0, v[138:139]
	s_add_i32 m0, s21, 0xe000
	s_nop 0
	global_load_lds_dwordx4 v[144:145], off
	s_waitcnt vmcnt(8)
	s_waitcnt lgkmcnt(0)
	s_setprio 1
	s_barrier
	v_mfma_f32_16x16x32_bf16 v[124:127], v[152:155], v[188:191], v[124:127]
	v_mfma_f32_16x16x32_bf16 v[120:123], v[160:163], v[188:191], v[120:123]
	v_mfma_f32_16x16x32_bf16 v[108:111], v[152:155], v[196:199], v[108:111]
	v_mfma_f32_16x16x32_bf16 v[104:107], v[160:163], v[196:199], v[104:107]
	v_mfma_f32_16x16x32_bf16 v[92:95], v[152:155], v[204:207], v[92:95]
	v_mfma_f32_16x16x32_bf16 v[88:91], v[160:163], v[204:207], v[88:91]
	v_mfma_f32_16x16x32_bf16 v[76:79], v[152:155], v[212:215], v[76:79]
	v_mfma_f32_16x16x32_bf16 v[72:75], v[160:163], v[212:215], v[72:75]
	v_mfma_f32_16x16x32_bf16 v[124:127], v[156:159], v[192:195], v[124:127]
	v_mfma_f32_16x16x32_bf16 v[120:123], v[164:167], v[192:195], v[120:123]
	v_mfma_f32_16x16x32_bf16 v[108:111], v[156:159], v[200:203], v[108:111]
	v_mfma_f32_16x16x32_bf16 v[104:107], v[164:167], v[200:203], v[104:107]
	v_mfma_f32_16x16x32_bf16 v[92:95], v[156:159], v[208:211], v[92:95]
	v_mfma_f32_16x16x32_bf16 v[88:91], v[164:167], v[208:211], v[88:91]
	v_mfma_f32_16x16x32_bf16 v[76:79], v[156:159], v[216:219], v[76:79]
	v_mfma_f32_16x16x32_bf16 v[72:75], v[164:167], v[216:219], v[72:75]
	v_mfma_f32_16x16x32_bf16 v[116:119], v[168:171], v[188:191], v[116:119]
	v_mfma_f32_16x16x32_bf16 v[112:115], v[176:179], v[188:191], v[112:115]
	v_mfma_f32_16x16x32_bf16 v[100:103], v[168:171], v[196:199], v[100:103]
	v_mfma_f32_16x16x32_bf16 v[96:99], v[176:179], v[196:199], v[96:99]
	v_mfma_f32_16x16x32_bf16 v[84:87], v[168:171], v[204:207], v[84:87]
	v_mfma_f32_16x16x32_bf16 v[80:83], v[176:179], v[204:207], v[80:83]
	v_mfma_f32_16x16x32_bf16 v[68:71], v[168:171], v[212:215], v[68:71]
	v_mfma_f32_16x16x32_bf16 v[64:67], v[176:179], v[212:215], v[64:67]
	v_mfma_f32_16x16x32_bf16 v[116:119], v[172:175], v[192:195], v[116:119]
	v_mfma_f32_16x16x32_bf16 v[112:115], v[184:187], v[192:195], v[112:115]
	v_mfma_f32_16x16x32_bf16 v[100:103], v[172:175], v[200:203], v[100:103]
	v_mfma_f32_16x16x32_bf16 v[96:99], v[184:187], v[200:203], v[96:99]
	v_mfma_f32_16x16x32_bf16 v[84:87], v[172:175], v[208:211], v[84:87]
	v_mfma_f32_16x16x32_bf16 v[80:83], v[184:187], v[208:211], v[80:83]
	v_mfma_f32_16x16x32_bf16 v[68:71], v[172:175], v[216:219], v[68:71]
	v_mfma_f32_16x16x32_bf16 v[64:67], v[184:187], v[216:219], v[64:67]
	s_barrier
	s_setprio 0
	s_add_i32 s52, s43, s34
	v_lshl_add_u64 v[144:145], s[24:25], 0, v[130:131]
	s_mov_b32 m0, s52
	ds_read_b128 v[188:191], v151 offset:16384
	ds_read_b128 v[192:195], v151 offset:17408
	ds_read_b128 v[196:199], v151 offset:18432
	ds_read_b128 v[200:203], v151 offset:19456
	ds_read_b128 v[204:207], v151 offset:20480
	ds_read_b128 v[208:211], v151 offset:21504
	ds_read_b128 v[212:215], v151 offset:22528
	ds_read_b128 v[216:219], v151 offset:23552
	global_load_lds_dwordx4 v[144:145], off
	s_add_i32 m0, s52, 0x2000
	s_add_u32 s52, s24, 0x40000
	v_lshl_add_u64 v[180:181], s[24:25], 0, v[134:135]
	s_addc_u32 s53, s25, 0
	s_add_i32 s54, s44, s34
	global_load_lds_dwordx4 v[180:181], off
	v_lshl_add_u64 v[220:221], s[52:53], 0, v[130:131]
	s_mov_b32 m0, s54
	v_lshl_add_u64 v[222:223], s[26:27], 0, v[132:133]
	global_load_lds_dwordx4 v[220:221], off
	v_lshl_add_u64 v[220:221], s[52:53], 0, v[134:135]
	s_add_i32 m0, s54, 0x2000
	s_nop 0
	global_load_lds_dwordx4 v[220:221], off
	v_lshl_add_u64 v[220:221], s[26:27], 0, v[128:129]
	s_mov_b32 m0, s21
	s_nop 0
	global_load_lds_dwordx4 v[220:221], off
	s_mov_b32 m0, s36
	s_nop 0
	global_load_lds_dwordx4 v[222:223], off
	s_waitcnt vmcnt(8)
	s_waitcnt lgkmcnt(0)
	s_setprio 1
	s_barrier
	v_mfma_f32_16x16x32_bf16 v[60:63], v[152:155], v[188:191], v[60:63]
	v_mfma_f32_16x16x32_bf16 v[56:59], v[160:163], v[188:191], v[56:59]
	v_mfma_f32_16x16x32_bf16 v[44:47], v[152:155], v[196:199], v[44:47]
	v_mfma_f32_16x16x32_bf16 v[40:43], v[160:163], v[196:199], v[40:43]
	v_mfma_f32_16x16x32_bf16 v[28:31], v[152:155], v[204:207], v[28:31]
	v_mfma_f32_16x16x32_bf16 v[24:27], v[160:163], v[204:207], v[24:27]
	v_mfma_f32_16x16x32_bf16 v[12:15], v[152:155], v[212:215], v[12:15]
	v_mfma_f32_16x16x32_bf16 v[8:11], v[160:163], v[212:215], v[8:11]
	v_mfma_f32_16x16x32_bf16 v[60:63], v[156:159], v[192:195], v[60:63]
	v_mfma_f32_16x16x32_bf16 v[56:59], v[164:167], v[192:195], v[56:59]
	v_mfma_f32_16x16x32_bf16 v[44:47], v[156:159], v[200:203], v[44:47]
	v_mfma_f32_16x16x32_bf16 v[40:43], v[164:167], v[200:203], v[40:43]
	v_mfma_f32_16x16x32_bf16 v[28:31], v[156:159], v[208:211], v[28:31]
	v_mfma_f32_16x16x32_bf16 v[24:27], v[164:167], v[208:211], v[24:27]
	v_mfma_f32_16x16x32_bf16 v[12:15], v[156:159], v[216:219], v[12:15]
	v_mfma_f32_16x16x32_bf16 v[8:11], v[164:167], v[216:219], v[8:11]
	v_mfma_f32_16x16x32_bf16 v[52:55], v[168:171], v[188:191], v[52:55]
	v_mfma_f32_16x16x32_bf16 v[48:51], v[176:179], v[188:191], v[48:51]
	v_mfma_f32_16x16x32_bf16 v[36:39], v[168:171], v[196:199], v[36:39]
	v_mfma_f32_16x16x32_bf16 v[32:35], v[176:179], v[196:199], v[32:35]
	v_mfma_f32_16x16x32_bf16 v[20:23], v[168:171], v[204:207], v[20:23]
	v_mfma_f32_16x16x32_bf16 v[16:19], v[176:179], v[204:207], v[16:19]
	v_mfma_f32_16x16x32_bf16 v[4:7], v[168:171], v[212:215], v[4:7]
	v_mfma_f32_16x16x32_bf16 v[0:3], v[176:179], v[212:215], v[0:3]
	v_mfma_f32_16x16x32_bf16 v[52:55], v[172:175], v[192:195], v[52:55]
	v_mfma_f32_16x16x32_bf16 v[48:51], v[184:187], v[192:195], v[48:51]
	v_mfma_f32_16x16x32_bf16 v[36:39], v[172:175], v[200:203], v[36:39]
	v_mfma_f32_16x16x32_bf16 v[32:35], v[184:187], v[200:203], v[32:35]
	v_mfma_f32_16x16x32_bf16 v[20:23], v[172:175], v[208:211], v[20:23]
	v_mfma_f32_16x16x32_bf16 v[16:19], v[184:187], v[208:211], v[16:19]
	v_mfma_f32_16x16x32_bf16 v[4:7], v[172:175], v[216:219], v[4:7]
	v_mfma_f32_16x16x32_bf16 v[0:3], v[184:187], v[216:219], v[0:3]
	s_barrier
	s_setprio 0
	s_add_i32 s52, 0, 0x18000
	s_add_i32 s53, 0, 0x1c000
	v_add_u32_e32 v164, s52, v147
	v_add_u32_e32 v183, s53, v147
	ds_read_b128 v[152:155], v164
	ds_read_b128 v[156:159], v164 offset:1024
	ds_read_b128 v[160:163], v164 offset:2048
	ds_read_b128 v[164:167], v164 offset:3072
	ds_read_b128 v[168:171], v183
	ds_read_b128 v[172:175], v183 offset:1024
	ds_read_b128 v[176:179], v183 offset:2048
	ds_read_b128 v[184:187], v183 offset:3072
	s_add_u32 s26, s26, 0x40000
	s_addc_u32 s27, s27, 0
	s_mov_b32 m0, s37
	v_lshl_add_u64 v[224:225], s[26:27], 0, v[128:129]
	ds_read_b128 v[188:191], v151 offset:32768
	ds_read_b128 v[192:195], v151 offset:33792
	ds_read_b128 v[196:199], v151 offset:34816
	ds_read_b128 v[200:203], v151 offset:35840
	ds_read_b128 v[204:207], v151 offset:36864
	ds_read_b128 v[208:211], v151 offset:37888
	ds_read_b128 v[212:215], v151 offset:38912
	ds_read_b128 v[216:219], v151 offset:39936
	global_load_lds_dwordx4 v[224:225], off
	v_lshl_add_u64 v[224:225], s[26:27], 0, v[132:133]
	s_mov_b32 m0, s38
	s_nop 0
	global_load_lds_dwordx4 v[224:225], off
	s_waitcnt vmcnt(8)
	s_waitcnt lgkmcnt(0)
	s_setprio 1
	s_barrier
	v_mfma_f32_16x16x32_bf16 v[124:127], v[152:155], v[188:191], v[124:127]
	v_mfma_f32_16x16x32_bf16 v[120:123], v[160:163], v[188:191], v[120:123]
	v_mfma_f32_16x16x32_bf16 v[108:111], v[152:155], v[196:199], v[108:111]
	v_mfma_f32_16x16x32_bf16 v[104:107], v[160:163], v[196:199], v[104:107]
	v_mfma_f32_16x16x32_bf16 v[92:95], v[152:155], v[204:207], v[92:95]
	v_mfma_f32_16x16x32_bf16 v[88:91], v[160:163], v[204:207], v[88:91]
	v_mfma_f32_16x16x32_bf16 v[76:79], v[152:155], v[212:215], v[76:79]
	v_mfma_f32_16x16x32_bf16 v[72:75], v[160:163], v[212:215], v[72:75]
	v_mfma_f32_16x16x32_bf16 v[124:127], v[156:159], v[192:195], v[124:127]
	v_mfma_f32_16x16x32_bf16 v[120:123], v[164:167], v[192:195], v[120:123]
	v_mfma_f32_16x16x32_bf16 v[108:111], v[156:159], v[200:203], v[108:111]
	v_mfma_f32_16x16x32_bf16 v[104:107], v[164:167], v[200:203], v[104:107]
	v_mfma_f32_16x16x32_bf16 v[92:95], v[156:159], v[208:211], v[92:95]
	v_mfma_f32_16x16x32_bf16 v[88:91], v[164:167], v[208:211], v[88:91]
	v_mfma_f32_16x16x32_bf16 v[76:79], v[156:159], v[216:219], v[76:79]
	v_mfma_f32_16x16x32_bf16 v[72:75], v[164:167], v[216:219], v[72:75]
	v_mfma_f32_16x16x32_bf16 v[116:119], v[168:171], v[188:191], v[116:119]
	v_mfma_f32_16x16x32_bf16 v[112:115], v[176:179], v[188:191], v[112:115]
	v_mfma_f32_16x16x32_bf16 v[100:103], v[168:171], v[196:199], v[100:103]
	v_mfma_f32_16x16x32_bf16 v[96:99], v[176:179], v[196:199], v[96:99]
	v_mfma_f32_16x16x32_bf16 v[84:87], v[168:171], v[204:207], v[84:87]
	v_mfma_f32_16x16x32_bf16 v[80:83], v[176:179], v[204:207], v[80:83]
	v_mfma_f32_16x16x32_bf16 v[68:71], v[168:171], v[212:215], v[68:71]
	v_mfma_f32_16x16x32_bf16 v[64:67], v[176:179], v[212:215], v[64:67]
	v_mfma_f32_16x16x32_bf16 v[116:119], v[172:175], v[192:195], v[116:119]
	v_mfma_f32_16x16x32_bf16 v[112:115], v[184:187], v[192:195], v[112:115]
	v_mfma_f32_16x16x32_bf16 v[100:103], v[172:175], v[200:203], v[100:103]
	v_mfma_f32_16x16x32_bf16 v[96:99], v[184:187], v[200:203], v[96:99]
	v_mfma_f32_16x16x32_bf16 v[84:87], v[172:175], v[208:211], v[84:87]
	v_mfma_f32_16x16x32_bf16 v[80:83], v[184:187], v[208:211], v[80:83]
	v_mfma_f32_16x16x32_bf16 v[68:71], v[172:175], v[216:219], v[68:71]
	v_mfma_f32_16x16x32_bf16 v[64:67], v[184:187], v[216:219], v[64:67]
	s_barrier
	s_setprio 0
	s_add_i32 s26, s52, s34
	v_lshl_add_u64 v[144:145], v[144:145], 0, s[8:9]
	s_mov_b32 m0, s26
	ds_read_b128 v[188:191], v151 offset:49152
	ds_read_b128 v[192:195], v151 offset:50176
	ds_read_b128 v[196:199], v151 offset:51200
	ds_read_b128 v[200:203], v151 offset:52224
	ds_read_b128 v[204:207], v151 offset:53248
	ds_read_b128 v[208:211], v151 offset:54272
	ds_read_b128 v[212:215], v151 offset:55296
	ds_read_b128 v[216:219], v151 offset:56320
	global_load_lds_dwordx4 v[144:145], off
	s_add_i32 m0, s26, 0x2000
	s_add_u32 s24, s24, 0x40080
	v_lshl_add_u64 v[144:145], v[180:181], 0, s[8:9]
	s_addc_u32 s25, s25, 0
	s_add_i32 s26, s53, s34
	global_load_lds_dwordx4 v[144:145], off
	v_lshl_add_u64 v[144:145], s[24:25], 0, v[130:131]
	s_mov_b32 m0, s26
	s_nop 0
	global_load_lds_dwordx4 v[144:145], off
	v_lshl_add_u64 v[144:145], s[24:25], 0, v[134:135]
	s_add_i32 m0, s26, 0x2000
	s_nop 0
	global_load_lds_dwordx4 v[144:145], off
	v_lshl_add_u64 v[144:145], v[220:221], 0, s[8:9]
	s_mov_b32 m0, s41
	s_nop 0
	global_load_lds_dwordx4 v[144:145], off
	v_lshl_add_u64 v[144:145], v[222:223], 0, s[8:9]
	s_mov_b32 m0, s42
	s_nop 0
	global_load_lds_dwordx4 v[144:145], off
	s_waitcnt vmcnt(8)
	s_waitcnt lgkmcnt(0)
	s_setprio 1
	s_barrier
	v_mfma_f32_16x16x32_bf16 v[60:63], v[152:155], v[188:191], v[60:63]
	v_mfma_f32_16x16x32_bf16 v[56:59], v[160:163], v[188:191], v[56:59]
	v_mfma_f32_16x16x32_bf16 v[44:47], v[152:155], v[196:199], v[44:47]
	v_mfma_f32_16x16x32_bf16 v[40:43], v[160:163], v[196:199], v[40:43]
	v_mfma_f32_16x16x32_bf16 v[28:31], v[152:155], v[204:207], v[28:31]
	v_mfma_f32_16x16x32_bf16 v[24:27], v[160:163], v[204:207], v[24:27]
	v_mfma_f32_16x16x32_bf16 v[12:15], v[152:155], v[212:215], v[12:15]
	v_mfma_f32_16x16x32_bf16 v[8:11], v[160:163], v[212:215], v[8:11]
	v_mfma_f32_16x16x32_bf16 v[60:63], v[156:159], v[192:195], v[60:63]
	v_mfma_f32_16x16x32_bf16 v[56:59], v[164:167], v[192:195], v[56:59]
	v_mfma_f32_16x16x32_bf16 v[44:47], v[156:159], v[200:203], v[44:47]
	v_mfma_f32_16x16x32_bf16 v[40:43], v[164:167], v[200:203], v[40:43]
	v_mfma_f32_16x16x32_bf16 v[28:31], v[156:159], v[208:211], v[28:31]
	v_mfma_f32_16x16x32_bf16 v[24:27], v[164:167], v[208:211], v[24:27]
	v_mfma_f32_16x16x32_bf16 v[12:15], v[156:159], v[216:219], v[12:15]
	v_mfma_f32_16x16x32_bf16 v[8:11], v[164:167], v[216:219], v[8:11]
	v_mfma_f32_16x16x32_bf16 v[52:55], v[168:171], v[188:191], v[52:55]
	v_mfma_f32_16x16x32_bf16 v[48:51], v[176:179], v[188:191], v[48:51]
	v_mfma_f32_16x16x32_bf16 v[36:39], v[168:171], v[196:199], v[36:39]
	v_mfma_f32_16x16x32_bf16 v[32:35], v[176:179], v[196:199], v[32:35]
	v_mfma_f32_16x16x32_bf16 v[20:23], v[168:171], v[204:207], v[20:23]
	v_mfma_f32_16x16x32_bf16 v[16:19], v[176:179], v[204:207], v[16:19]
	v_mfma_f32_16x16x32_bf16 v[4:7], v[168:171], v[212:215], v[4:7]
	v_mfma_f32_16x16x32_bf16 v[0:3], v[176:179], v[212:215], v[0:3]
	v_mfma_f32_16x16x32_bf16 v[52:55], v[172:175], v[192:195], v[52:55]
	v_mfma_f32_16x16x32_bf16 v[48:51], v[184:187], v[192:195], v[48:51]
	v_mfma_f32_16x16x32_bf16 v[36:39], v[172:175], v[200:203], v[36:39]
	v_mfma_f32_16x16x32_bf16 v[32:35], v[184:187], v[200:203], v[32:35]
	v_mfma_f32_16x16x32_bf16 v[20:23], v[172:175], v[208:211], v[20:23]
	v_mfma_f32_16x16x32_bf16 v[16:19], v[184:187], v[208:211], v[16:19]
	v_mfma_f32_16x16x32_bf16 v[4:7], v[172:175], v[216:219], v[4:7]
	v_mfma_f32_16x16x32_bf16 v[0:3], v[184:187], v[216:219], v[0:3]
	s_barrier
	s_setprio 0
	s_add_i32 s51, s51, 2
	s_add_u32 s22, s22, 0x100
	s_addc_u32 s23, s23, 0
	s_add_u32 s49, s49, 0x100
	s_addc_u32 s50, s50, 0
	s_cmp_gt_u32 s51, 13
	s_cbranch_scc0 .LBB0_259
	s_and_b64 vcc, exec, s[10:11]
	s_cbranch_vccz .LBB0_262
	s_barrier

.LBB0_338:
	ds_read_b128 v[150:153], v147
	ds_read_b128 v[154:157], v147 offset:1024
	ds_read_b128 v[158:161], v147 offset:2048
	ds_read_b128 v[162:165], v147 offset:3072
	ds_read_b128 v[166:169], v148
	ds_read_b128 v[170:173], v148 offset:1024
	ds_read_b128 v[174:177], v148 offset:2048
	ds_read_b128 v[178:181], v148 offset:3072
	s_add_u32 s26, s24, 0xfff50080
	s_addc_u32 s27, s25, -1
	s_cmp_eq_u32 s57, 40
	s_cselect_b32 s29, s5, s27
	s_cselect_b32 s28, s4, s26
	s_cselect_b32 s27, s23, s56
	s_cselect_b32 s26, s22, s55
	v_lshl_add_u64 v[216:217], s[24:25], 0, v[136:137]
	s_add_i32 m0, s37, 0xc000
	ds_read_b128 v[184:187], v149
	ds_read_b128 v[188:191], v149 offset:1024
	ds_read_b128 v[192:195], v149 offset:2048
	ds_read_b128 v[196:199], v149 offset:3072
	ds_read_b128 v[200:203], v149 offset:4096
	ds_read_b128 v[204:207], v149 offset:5120
	ds_read_b128 v[208:211], v149 offset:6144
	ds_read_b128 v[212:215], v149 offset:7168
	global_load_lds_dwordx4 v[216:217], off
	v_lshl_add_u64 v[216:217], s[24:25], 0, v[138:139]
	s_add_i32 m0, s37, 0xe000
	s_nop 0
	global_load_lds_dwordx4 v[216:217], off
	s_waitcnt vmcnt(8)
	s_waitcnt lgkmcnt(0)
	s_setprio 1
	s_barrier
	v_mfma_f32_16x16x32_bf16 v[124:127], v[150:153], v[184:187], v[124:127]
	v_mfma_f32_16x16x32_bf16 v[120:123], v[158:161], v[184:187], v[120:123]
	v_mfma_f32_16x16x32_bf16 v[116:119], v[150:153], v[192:195], v[116:119]
	v_mfma_f32_16x16x32_bf16 v[112:115], v[158:161], v[192:195], v[112:115]
	v_mfma_f32_16x16x32_bf16 v[100:103], v[150:153], v[200:203], v[100:103]
	v_mfma_f32_16x16x32_bf16 v[96:99], v[158:161], v[200:203], v[96:99]
	v_mfma_f32_16x16x32_bf16 v[84:87], v[150:153], v[208:211], v[84:87]
	v_mfma_f32_16x16x32_bf16 v[80:83], v[158:161], v[208:211], v[80:83]
	v_mfma_f32_16x16x32_bf16 v[124:127], v[154:157], v[188:191], v[124:127]
	v_mfma_f32_16x16x32_bf16 v[120:123], v[162:165], v[188:191], v[120:123]
	v_mfma_f32_16x16x32_bf16 v[116:119], v[154:157], v[196:199], v[116:119]
	v_mfma_f32_16x16x32_bf16 v[112:115], v[162:165], v[196:199], v[112:115]
	v_mfma_f32_16x16x32_bf16 v[100:103], v[154:157], v[204:207], v[100:103]
	v_mfma_f32_16x16x32_bf16 v[96:99], v[162:165], v[204:207], v[96:99]
	v_mfma_f32_16x16x32_bf16 v[84:87], v[154:157], v[212:215], v[84:87]
	v_mfma_f32_16x16x32_bf16 v[80:83], v[162:165], v[212:215], v[80:83]
	v_mfma_f32_16x16x32_bf16 v[108:111], v[166:169], v[184:187], v[108:111]
	v_mfma_f32_16x16x32_bf16 v[104:107], v[174:177], v[184:187], v[104:107]
	v_mfma_f32_16x16x32_bf16 v[92:95], v[166:169], v[192:195], v[92:95]
	v_mfma_f32_16x16x32_bf16 v[88:91], v[174:177], v[192:195], v[88:91]
	v_mfma_f32_16x16x32_bf16 v[76:79], v[166:169], v[200:203], v[76:79]
	v_mfma_f32_16x16x32_bf16 v[72:75], v[174:177], v[200:203], v[72:75]
	v_mfma_f32_16x16x32_bf16 v[68:71], v[166:169], v[208:211], v[68:71]
	v_mfma_f32_16x16x32_bf16 v[64:67], v[174:177], v[208:211], v[64:67]
	v_mfma_f32_16x16x32_bf16 v[108:111], v[170:173], v[188:191], v[108:111]
	v_mfma_f32_16x16x32_bf16 v[104:107], v[178:181], v[188:191], v[104:107]
	v_mfma_f32_16x16x32_bf16 v[92:95], v[170:173], v[196:199], v[92:95]
	v_mfma_f32_16x16x32_bf16 v[88:91], v[178:181], v[196:199], v[88:91]
	v_mfma_f32_16x16x32_bf16 v[76:79], v[170:173], v[204:207], v[76:79]
	v_mfma_f32_16x16x32_bf16 v[72:75], v[178:181], v[204:207], v[72:75]
	v_mfma_f32_16x16x32_bf16 v[68:71], v[170:173], v[212:215], v[68:71]
	v_mfma_f32_16x16x32_bf16 v[64:67], v[178:181], v[212:215], v[64:67]
	s_barrier
	s_setprio 0
	s_add_i32 s58, s45, s36
	v_lshl_add_u64 v[216:217], s[26:27], 0, v[130:131]
	s_mov_b32 m0, s58
	ds_read_b128 v[184:187], v149 offset:16384
	ds_read_b128 v[188:191], v149 offset:17408
	ds_read_b128 v[192:195], v149 offset:18432
	ds_read_b128 v[196:199], v149 offset:19456
	ds_read_b128 v[200:203], v149 offset:20480
	ds_read_b128 v[204:207], v149 offset:21504
	ds_read_b128 v[208:211], v149 offset:22528
	ds_read_b128 v[212:215], v149 offset:23552
	global_load_lds_dwordx4 v[216:217], off
	s_add_i32 m0, s58, 0x2000
	s_add_u32 s58, s26, 0xb0000
	v_lshl_add_u64 v[218:219], s[26:27], 0, v[134:135]
	s_addc_u32 s59, s27, 0
	s_add_i32 s60, s46, s36
	global_load_lds_dwordx4 v[218:219], off
	v_lshl_add_u64 v[220:221], s[58:59], 0, v[130:131]
	s_mov_b32 m0, s60
	v_lshl_add_u64 v[222:223], s[28:29], 0, v[132:133]
	global_load_lds_dwordx4 v[220:221], off
	v_lshl_add_u64 v[220:221], s[58:59], 0, v[134:135]
	s_add_i32 m0, s60, 0x2000
	s_nop 0
	global_load_lds_dwordx4 v[220:221], off
	v_lshl_add_u64 v[220:221], s[28:29], 0, v[128:129]
	s_mov_b32 m0, s37
	s_nop 0
	global_load_lds_dwordx4 v[220:221], off
	s_mov_b32 m0, s38
	s_nop 0
	global_load_lds_dwordx4 v[222:223], off
	s_waitcnt vmcnt(8)
	s_waitcnt lgkmcnt(0)
	s_setprio 1
	s_barrier
	v_mfma_f32_16x16x32_bf16 v[60:63], v[150:153], v[184:187], v[60:63]
	v_mfma_f32_16x16x32_bf16 v[56:59], v[158:161], v[184:187], v[56:59]
	v_mfma_f32_16x16x32_bf16 v[52:55], v[150:153], v[192:195], v[52:55]
	v_mfma_f32_16x16x32_bf16 v[48:51], v[158:161], v[192:195], v[48:51]
	v_mfma_f32_16x16x32_bf16 v[36:39], v[150:153], v[200:203], v[36:39]
	v_mfma_f32_16x16x32_bf16 v[32:35], v[158:161], v[200:203], v[32:35]
	v_mfma_f32_16x16x32_bf16 v[20:23], v[150:153], v[208:211], v[20:23]
	v_mfma_f32_16x16x32_bf16 v[16:19], v[158:161], v[208:211], v[16:19]
	v_mfma_f32_16x16x32_bf16 v[60:63], v[154:157], v[188:191], v[60:63]
	v_mfma_f32_16x16x32_bf16 v[56:59], v[162:165], v[188:191], v[56:59]
	v_mfma_f32_16x16x32_bf16 v[52:55], v[154:157], v[196:199], v[52:55]
	v_mfma_f32_16x16x32_bf16 v[48:51], v[162:165], v[196:199], v[48:51]
	v_mfma_f32_16x16x32_bf16 v[36:39], v[154:157], v[204:207], v[36:39]
	v_mfma_f32_16x16x32_bf16 v[32:35], v[162:165], v[204:207], v[32:35]
	v_mfma_f32_16x16x32_bf16 v[20:23], v[154:157], v[212:215], v[20:23]
	v_mfma_f32_16x16x32_bf16 v[16:19], v[162:165], v[212:215], v[16:19]
	v_mfma_f32_16x16x32_bf16 v[44:47], v[166:169], v[184:187], v[44:47]
	v_mfma_f32_16x16x32_bf16 v[40:43], v[174:177], v[184:187], v[40:43]
	v_mfma_f32_16x16x32_bf16 v[28:31], v[166:169], v[192:195], v[28:31]
	v_mfma_f32_16x16x32_bf16 v[24:27], v[174:177], v[192:195], v[24:27]
	v_mfma_f32_16x16x32_bf16 v[12:15], v[166:169], v[200:203], v[12:15]
	v_mfma_f32_16x16x32_bf16 v[8:11], v[174:177], v[200:203], v[8:11]
	v_mfma_f32_16x16x32_bf16 v[4:7], v[166:169], v[208:211], v[4:7]
	v_mfma_f32_16x16x32_bf16 v[0:3], v[174:177], v[208:211], v[0:3]
	v_mfma_f32_16x16x32_bf16 v[44:47], v[170:173], v[188:191], v[44:47]
	v_mfma_f32_16x16x32_bf16 v[40:43], v[178:181], v[188:191], v[40:43]
	v_mfma_f32_16x16x32_bf16 v[28:31], v[170:173], v[196:199], v[28:31]
	v_mfma_f32_16x16x32_bf16 v[24:27], v[178:181], v[196:199], v[24:27]
	v_mfma_f32_16x16x32_bf16 v[12:15], v[170:173], v[204:207], v[12:15]
	v_mfma_f32_16x16x32_bf16 v[8:11], v[178:181], v[204:207], v[8:11]
	v_mfma_f32_16x16x32_bf16 v[4:7], v[170:173], v[212:215], v[4:7]
	v_mfma_f32_16x16x32_bf16 v[0:3], v[178:181], v[212:215], v[0:3]
	s_barrier
	s_setprio 0
	s_add_i32 s58, 0, 0x18000
	s_add_i32 s59, 0, 0x1c000
	v_add_u32_e32 v162, s58, v145
	v_add_u32_e32 v178, s59, v145
	ds_read_b128 v[150:153], v162
	ds_read_b128 v[154:157], v162 offset:1024
	ds_read_b128 v[158:161], v162 offset:2048
	ds_read_b128 v[162:165], v162 offset:3072
	ds_read_b128 v[166:169], v178
	ds_read_b128 v[170:173], v178 offset:1024
	ds_read_b128 v[174:177], v178 offset:2048
	ds_read_b128 v[178:181], v178 offset:3072
	s_add_u32 s28, s28, 0xb0000
	s_addc_u32 s29, s29, 0
	s_mov_b32 m0, s39
	v_lshl_add_u64 v[224:225], s[28:29], 0, v[128:129]
	ds_read_b128 v[184:187], v149 offset:32768
	ds_read_b128 v[188:191], v149 offset:33792
	ds_read_b128 v[192:195], v149 offset:34816
	ds_read_b128 v[196:199], v149 offset:35840
	ds_read_b128 v[200:203], v149 offset:36864
	ds_read_b128 v[204:207], v149 offset:37888
	ds_read_b128 v[208:211], v149 offset:38912
	ds_read_b128 v[212:215], v149 offset:39936
	global_load_lds_dwordx4 v[224:225], off
	v_lshl_add_u64 v[224:225], s[28:29], 0, v[132:133]
	s_mov_b32 m0, s40
	s_nop 0
	global_load_lds_dwordx4 v[224:225], off
	s_waitcnt vmcnt(8)
	s_waitcnt lgkmcnt(0)
	s_setprio 1
	s_barrier
	v_mfma_f32_16x16x32_bf16 v[124:127], v[150:153], v[184:187], v[124:127]
	v_mfma_f32_16x16x32_bf16 v[120:123], v[158:161], v[184:187], v[120:123]
	v_mfma_f32_16x16x32_bf16 v[116:119], v[150:153], v[192:195], v[116:119]
	v_mfma_f32_16x16x32_bf16 v[112:115], v[158:161], v[192:195], v[112:115]
	v_mfma_f32_16x16x32_bf16 v[100:103], v[150:153], v[200:203], v[100:103]
	v_mfma_f32_16x16x32_bf16 v[96:99], v[158:161], v[200:203], v[96:99]
	v_mfma_f32_16x16x32_bf16 v[84:87], v[150:153], v[208:211], v[84:87]
	v_mfma_f32_16x16x32_bf16 v[80:83], v[158:161], v[208:211], v[80:83]
	v_mfma_f32_16x16x32_bf16 v[124:127], v[154:157], v[188:191], v[124:127]
	v_mfma_f32_16x16x32_bf16 v[120:123], v[162:165], v[188:191], v[120:123]
	v_mfma_f32_16x16x32_bf16 v[116:119], v[154:157], v[196:199], v[116:119]
	v_mfma_f32_16x16x32_bf16 v[112:115], v[162:165], v[196:199], v[112:115]
	v_mfma_f32_16x16x32_bf16 v[100:103], v[154:157], v[204:207], v[100:103]
	v_mfma_f32_16x16x32_bf16 v[96:99], v[162:165], v[204:207], v[96:99]
	v_mfma_f32_16x16x32_bf16 v[84:87], v[154:157], v[212:215], v[84:87]
	v_mfma_f32_16x16x32_bf16 v[80:83], v[162:165], v[212:215], v[80:83]
	v_mfma_f32_16x16x32_bf16 v[108:111], v[166:169], v[184:187], v[108:111]
	v_mfma_f32_16x16x32_bf16 v[104:107], v[174:177], v[184:187], v[104:107]
	v_mfma_f32_16x16x32_bf16 v[92:95], v[166:169], v[192:195], v[92:95]
	v_mfma_f32_16x16x32_bf16 v[88:91], v[174:177], v[192:195], v[88:91]
	v_mfma_f32_16x16x32_bf16 v[76:79], v[166:169], v[200:203], v[76:79]
	v_mfma_f32_16x16x32_bf16 v[72:75], v[174:177], v[200:203], v[72:75]
	v_mfma_f32_16x16x32_bf16 v[68:71], v[166:169], v[208:211], v[68:71]
	v_mfma_f32_16x16x32_bf16 v[64:67], v[174:177], v[208:211], v[64:67]
	v_mfma_f32_16x16x32_bf16 v[108:111], v[170:173], v[188:191], v[108:111]
	v_mfma_f32_16x16x32_bf16 v[104:107], v[178:181], v[188:191], v[104:107]
	v_mfma_f32_16x16x32_bf16 v[92:95], v[170:173], v[196:199], v[92:95]
	v_mfma_f32_16x16x32_bf16 v[88:91], v[178:181], v[196:199], v[88:91]
	v_mfma_f32_16x16x32_bf16 v[76:79], v[170:173], v[204:207], v[76:79]
	v_mfma_f32_16x16x32_bf16 v[72:75], v[178:181], v[204:207], v[72:75]
	v_mfma_f32_16x16x32_bf16 v[68:71], v[170:173], v[212:215], v[68:71]
	v_mfma_f32_16x16x32_bf16 v[64:67], v[178:181], v[212:215], v[64:67]
	s_barrier
	s_setprio 0
	s_add_i32 s28, s58, s36
	v_lshl_add_u64 v[216:217], v[216:217], 0, s[10:11]
	s_mov_b32 m0, s28
	ds_read_b128 v[184:187], v149 offset:49152
	ds_read_b128 v[188:191], v149 offset:50176
	ds_read_b128 v[192:195], v149 offset:51200
	ds_read_b128 v[196:199], v149 offset:52224
	ds_read_b128 v[200:203], v149 offset:53248
	ds_read_b128 v[204:207], v149 offset:54272
	ds_read_b128 v[208:211], v149 offset:55296
	ds_read_b128 v[212:215], v149 offset:56320
	global_load_lds_dwordx4 v[216:217], off
	s_add_i32 m0, s28, 0x2000
	s_add_u32 s26, s26, 0xb0080
	v_lshl_add_u64 v[216:217], v[218:219], 0, s[10:11]
	s_addc_u32 s27, s27, 0
	s_add_i32 s28, s59, s36
	global_load_lds_dwordx4 v[216:217], off
	v_lshl_add_u64 v[216:217], s[26:27], 0, v[130:131]
	s_mov_b32 m0, s28
	s_nop 0
	global_load_lds_dwordx4 v[216:217], off
	v_lshl_add_u64 v[216:217], s[26:27], 0, v[134:135]
	s_add_i32 m0, s28, 0x2000
	s_nop 0
	global_load_lds_dwordx4 v[216:217], off
	v_lshl_add_u64 v[216:217], v[220:221], 0, s[10:11]
	s_mov_b32 m0, s43
	s_nop 0
	global_load_lds_dwordx4 v[216:217], off
	v_lshl_add_u64 v[216:217], v[222:223], 0, s[10:11]
	s_mov_b32 m0, s44
	s_nop 0
	global_load_lds_dwordx4 v[216:217], off
	s_waitcnt vmcnt(8)
	s_waitcnt lgkmcnt(0)
	s_setprio 1
	s_barrier
	v_mfma_f32_16x16x32_bf16 v[60:63], v[150:153], v[184:187], v[60:63]
	v_mfma_f32_16x16x32_bf16 v[56:59], v[158:161], v[184:187], v[56:59]
	v_mfma_f32_16x16x32_bf16 v[52:55], v[150:153], v[192:195], v[52:55]
	v_mfma_f32_16x16x32_bf16 v[48:51], v[158:161], v[192:195], v[48:51]
	v_mfma_f32_16x16x32_bf16 v[36:39], v[150:153], v[200:203], v[36:39]
	v_mfma_f32_16x16x32_bf16 v[32:35], v[158:161], v[200:203], v[32:35]
	v_mfma_f32_16x16x32_bf16 v[20:23], v[150:153], v[208:211], v[20:23]
	v_mfma_f32_16x16x32_bf16 v[16:19], v[158:161], v[208:211], v[16:19]
	v_mfma_f32_16x16x32_bf16 v[60:63], v[154:157], v[188:191], v[60:63]
	v_mfma_f32_16x16x32_bf16 v[56:59], v[162:165], v[188:191], v[56:59]
	v_mfma_f32_16x16x32_bf16 v[52:55], v[154:157], v[196:199], v[52:55]
	v_mfma_f32_16x16x32_bf16 v[48:51], v[162:165], v[196:199], v[48:51]
	v_mfma_f32_16x16x32_bf16 v[36:39], v[154:157], v[204:207], v[36:39]
	v_mfma_f32_16x16x32_bf16 v[32:35], v[162:165], v[204:207], v[32:35]
	v_mfma_f32_16x16x32_bf16 v[20:23], v[154:157], v[212:215], v[20:23]
	v_mfma_f32_16x16x32_bf16 v[16:19], v[162:165], v[212:215], v[16:19]
	v_mfma_f32_16x16x32_bf16 v[44:47], v[166:169], v[184:187], v[44:47]
	v_mfma_f32_16x16x32_bf16 v[40:43], v[174:177], v[184:187], v[40:43]
	v_mfma_f32_16x16x32_bf16 v[28:31], v[166:169], v[192:195], v[28:31]
	v_mfma_f32_16x16x32_bf16 v[24:27], v[174:177], v[192:195], v[24:27]
	v_mfma_f32_16x16x32_bf16 v[12:15], v[166:169], v[200:203], v[12:15]
	v_mfma_f32_16x16x32_bf16 v[8:11], v[174:177], v[200:203], v[8:11]
	v_mfma_f32_16x16x32_bf16 v[4:7], v[166:169], v[208:211], v[4:7]
	v_mfma_f32_16x16x32_bf16 v[0:3], v[174:177], v[208:211], v[0:3]
	v_mfma_f32_16x16x32_bf16 v[44:47], v[170:173], v[188:191], v[44:47]
	v_mfma_f32_16x16x32_bf16 v[40:43], v[178:181], v[188:191], v[40:43]
	v_mfma_f32_16x16x32_bf16 v[28:31], v[170:173], v[196:199], v[28:31]
	v_mfma_f32_16x16x32_bf16 v[24:27], v[178:181], v[196:199], v[24:27]
	v_mfma_f32_16x16x32_bf16 v[12:15], v[170:173], v[204:207], v[12:15]
	v_mfma_f32_16x16x32_bf16 v[8:11], v[178:181], v[204:207], v[8:11]
	v_mfma_f32_16x16x32_bf16 v[4:7], v[170:173], v[212:215], v[4:7]
	v_mfma_f32_16x16x32_bf16 v[0:3], v[178:181], v[212:215], v[0:3]
	s_barrier
	s_setprio 0
	s_add_i32 s57, s57, 2
	s_add_u32 s24, s24, 0x100
	s_addc_u32 s25, s25, 0
	s_add_u32 s55, s55, 0x100
	s_addc_u32 s56, s56, 0
	s_cmp_gt_u32 s57, 41
	s_cbranch_scc0 .LBB0_338
	s_and_b64 vcc, exec, s[12:13]
	s_cbranch_vccz .LBB0_341
	s_barrier

.LBB0_475:
	ds_read_b128 v[150:153], v158
	ds_read_b128 v[162:165], v158 offset:1024
	ds_read_b128 v[166:169], v158 offset:2048
	ds_read_b128 v[170:173], v158 offset:3072
	ds_read_b128 v[174:177], v159
	ds_read_b128 v[178:181], v159 offset:1024
	ds_read_b128 v[184:187], v159 offset:2048
	ds_read_b128 v[188:191], v159 offset:3072
	s_add_u32 s48, s46, 0xfffc0080
	s_addc_u32 s49, s47, -1
	s_cmp_eq_u32 s77, 12
	s_cselect_b32 s51, s1, s49
	s_cselect_b32 s50, s39, s48
	s_cselect_b32 s49, s37, s76
	s_cselect_b32 s48, s45, s75
	v_lshl_add_u64 v[224:225], s[46:47], 0, v[142:143]
	s_add_i32 m0, s57, 0xc000
	ds_read_b128 v[192:195], v160
	ds_read_b128 v[196:199], v160 offset:1024
	ds_read_b128 v[200:203], v160 offset:2048
	ds_read_b128 v[204:207], v160 offset:3072
	ds_read_b128 v[208:211], v160 offset:4096
	ds_read_b128 v[212:215], v160 offset:5120
	ds_read_b128 v[216:219], v160 offset:6144
	ds_read_b128 v[220:223], v160 offset:7168
	global_load_lds_dwordx4 v[224:225], off
	v_lshl_add_u64 v[224:225], s[46:47], 0, v[144:145]
	s_add_i32 m0, s57, 0xe000
	s_nop 0
	global_load_lds_dwordx4 v[224:225], off
	s_waitcnt vmcnt(8)
	s_waitcnt lgkmcnt(0)
	s_setprio 1
	s_barrier
	v_mfma_f32_16x16x32_bf16 v[64:67], v[150:153], v[192:195], v[64:67]
	v_mfma_f32_16x16x32_bf16 v[28:31], v[166:169], v[192:195], v[28:31]
	v_mfma_f32_16x16x32_bf16 v[60:63], v[150:153], v[200:203], v[60:63]
	v_mfma_f32_16x16x32_bf16 v[24:27], v[166:169], v[200:203], v[24:27]
	v_mfma_f32_16x16x32_bf16 v[56:59], v[150:153], v[208:211], v[56:59]
	v_mfma_f32_16x16x32_bf16 v[20:23], v[166:169], v[208:211], v[20:23]
	v_mfma_f32_16x16x32_bf16 v[52:55], v[150:153], v[216:219], v[52:55]
	v_mfma_f32_16x16x32_bf16 v[16:19], v[166:169], v[216:219], v[16:19]
	v_mfma_f32_16x16x32_bf16 v[64:67], v[162:165], v[196:199], v[64:67]
	v_mfma_f32_16x16x32_bf16 v[28:31], v[170:173], v[196:199], v[28:31]
	v_mfma_f32_16x16x32_bf16 v[60:63], v[162:165], v[204:207], v[60:63]
	v_mfma_f32_16x16x32_bf16 v[24:27], v[170:173], v[204:207], v[24:27]
	v_mfma_f32_16x16x32_bf16 v[56:59], v[162:165], v[212:215], v[56:59]
	v_mfma_f32_16x16x32_bf16 v[20:23], v[170:173], v[212:215], v[20:23]
	v_mfma_f32_16x16x32_bf16 v[52:55], v[162:165], v[220:223], v[52:55]
	v_mfma_f32_16x16x32_bf16 v[16:19], v[170:173], v[220:223], v[16:19]
	v_mfma_f32_16x16x32_bf16 v[124:127], v[174:177], v[192:195], v[124:127]
	v_mfma_f32_16x16x32_bf16 v[120:123], v[184:187], v[192:195], v[120:123]
	v_mfma_f32_16x16x32_bf16 v[116:119], v[174:177], v[200:203], v[116:119]
	v_mfma_f32_16x16x32_bf16 v[112:115], v[184:187], v[200:203], v[112:115]
	v_mfma_f32_16x16x32_bf16 v[108:111], v[174:177], v[208:211], v[108:111]
	v_mfma_f32_16x16x32_bf16 v[104:107], v[184:187], v[208:211], v[104:107]
	v_mfma_f32_16x16x32_bf16 v[100:103], v[174:177], v[216:219], v[100:103]
	v_mfma_f32_16x16x32_bf16 v[96:99], v[184:187], v[216:219], v[96:99]
	v_mfma_f32_16x16x32_bf16 v[124:127], v[178:181], v[196:199], v[124:127]
	v_mfma_f32_16x16x32_bf16 v[120:123], v[188:191], v[196:199], v[120:123]
	v_mfma_f32_16x16x32_bf16 v[116:119], v[178:181], v[204:207], v[116:119]
	v_mfma_f32_16x16x32_bf16 v[112:115], v[188:191], v[204:207], v[112:115]
	v_mfma_f32_16x16x32_bf16 v[108:111], v[178:181], v[212:215], v[108:111]
	v_mfma_f32_16x16x32_bf16 v[104:107], v[188:191], v[212:215], v[104:107]
	v_mfma_f32_16x16x32_bf16 v[100:103], v[178:181], v[220:223], v[100:103]
	v_mfma_f32_16x16x32_bf16 v[96:99], v[188:191], v[220:223], v[96:99]
	s_barrier
	s_setprio 0
	s_add_i32 s78, s66, s56
	v_lshl_add_u64 v[224:225], s[48:49], 0, v[130:131]
	s_mov_b32 m0, s78
	ds_read_b128 v[192:195], v160 offset:16384
	ds_read_b128 v[196:199], v160 offset:17408
	ds_read_b128 v[200:203], v160 offset:18432
	ds_read_b128 v[204:207], v160 offset:19456
	ds_read_b128 v[208:211], v160 offset:20480
	ds_read_b128 v[212:215], v160 offset:21504
	ds_read_b128 v[216:219], v160 offset:22528
	ds_read_b128 v[220:223], v160 offset:23552
	global_load_lds_dwordx4 v[224:225], off
	s_add_i32 m0, s78, 0x2000
	s_add_u32 s78, s48, 0x40000
	v_lshl_add_u64 v[226:227], s[48:49], 0, v[134:135]
	s_addc_u32 s79, s49, 0
	s_add_i32 s80, s67, s56
	global_load_lds_dwordx4 v[226:227], off
	v_lshl_add_u64 v[228:229], s[78:79], 0, v[130:131]
	s_mov_b32 m0, s80
	v_lshl_add_u64 v[230:231], s[50:51], 0, v[132:133]
	global_load_lds_dwordx4 v[228:229], off
	v_lshl_add_u64 v[228:229], s[78:79], 0, v[134:135]
	s_add_i32 m0, s80, 0x2000
	s_nop 0
	global_load_lds_dwordx4 v[228:229], off
	v_lshl_add_u64 v[228:229], s[50:51], 0, v[128:129]
	s_mov_b32 m0, s57
	s_nop 0
	global_load_lds_dwordx4 v[228:229], off
	s_mov_b32 m0, s58
	s_nop 0
	global_load_lds_dwordx4 v[230:231], off
	s_waitcnt vmcnt(8)
	s_waitcnt lgkmcnt(0)
	s_setprio 1
	s_barrier
	v_mfma_f32_16x16x32_bf16 v[44:47], v[150:153], v[192:195], v[44:47]
	v_mfma_f32_16x16x32_bf16 v[12:15], v[166:169], v[192:195], v[12:15]
	v_mfma_f32_16x16x32_bf16 v[40:43], v[150:153], v[200:203], v[40:43]
	v_mfma_f32_16x16x32_bf16 v[8:11], v[166:169], v[200:203], v[8:11]
	v_mfma_f32_16x16x32_bf16 v[36:39], v[150:153], v[208:211], v[36:39]
	v_mfma_f32_16x16x32_bf16 v[4:7], v[166:169], v[208:211], v[4:7]
	v_mfma_f32_16x16x32_bf16 v[32:35], v[150:153], v[216:219], v[32:35]
	v_mfma_f32_16x16x32_bf16 v[0:3], v[166:169], v[216:219], v[0:3]
	v_mfma_f32_16x16x32_bf16 v[44:47], v[162:165], v[196:199], v[44:47]
	v_mfma_f32_16x16x32_bf16 v[12:15], v[170:173], v[196:199], v[12:15]
	v_mfma_f32_16x16x32_bf16 v[40:43], v[162:165], v[204:207], v[40:43]
	v_mfma_f32_16x16x32_bf16 v[8:11], v[170:173], v[204:207], v[8:11]
	v_mfma_f32_16x16x32_bf16 v[36:39], v[162:165], v[212:215], v[36:39]
	v_mfma_f32_16x16x32_bf16 v[4:7], v[170:173], v[212:215], v[4:7]
	v_mfma_f32_16x16x32_bf16 v[32:35], v[162:165], v[220:223], v[32:35]
	v_mfma_f32_16x16x32_bf16 v[0:3], v[170:173], v[220:223], v[0:3]
	v_mfma_f32_16x16x32_bf16 v[92:95], v[174:177], v[192:195], v[92:95]
	v_mfma_f32_16x16x32_bf16 v[88:91], v[184:187], v[192:195], v[88:91]
	v_mfma_f32_16x16x32_bf16 v[84:87], v[174:177], v[200:203], v[84:87]
	v_mfma_f32_16x16x32_bf16 v[80:83], v[184:187], v[200:203], v[80:83]
	v_mfma_f32_16x16x32_bf16 v[76:79], v[174:177], v[208:211], v[76:79]
	v_mfma_f32_16x16x32_bf16 v[72:75], v[184:187], v[208:211], v[72:75]
	v_mfma_f32_16x16x32_bf16 v[68:71], v[174:177], v[216:219], v[68:71]
	v_mfma_f32_16x16x32_bf16 v[48:51], v[184:187], v[216:219], v[48:51]
	v_mfma_f32_16x16x32_bf16 v[92:95], v[178:181], v[196:199], v[92:95]
	v_mfma_f32_16x16x32_bf16 v[88:91], v[188:191], v[196:199], v[88:91]
	v_mfma_f32_16x16x32_bf16 v[84:87], v[178:181], v[204:207], v[84:87]
	v_mfma_f32_16x16x32_bf16 v[80:83], v[188:191], v[204:207], v[80:83]
	v_mfma_f32_16x16x32_bf16 v[76:79], v[178:181], v[212:215], v[76:79]
	v_mfma_f32_16x16x32_bf16 v[72:75], v[188:191], v[212:215], v[72:75]
	v_mfma_f32_16x16x32_bf16 v[68:71], v[178:181], v[220:223], v[68:71]
	v_mfma_f32_16x16x32_bf16 v[48:51], v[188:191], v[220:223], v[48:51]
	s_barrier
	s_setprio 0
	s_add_i32 s78, 0, 0x18000
	v_add_u32_e32 v136, s78, v156
	s_add_i32 s79, 0, 0x1c000
	ds_read_b128 v[150:153], v136
	ds_read_b128 v[162:165], v136 offset:1024
	ds_read_b128 v[166:169], v136 offset:2048
	ds_read_b128 v[170:173], v136 offset:3072
	v_add_u32_e32 v136, s79, v156
	ds_read_b128 v[174:177], v136
	ds_read_b128 v[178:181], v136 offset:1024
	ds_read_b128 v[184:187], v136 offset:2048
	ds_read_b128 v[188:191], v136 offset:3072
	s_add_u32 s50, s50, 0x40000
	s_addc_u32 s51, s51, 0
	s_mov_b32 m0, s59
	v_lshl_add_u64 v[232:233], s[50:51], 0, v[128:129]
	ds_read_b128 v[192:195], v160 offset:32768
	ds_read_b128 v[196:199], v160 offset:33792
	ds_read_b128 v[200:203], v160 offset:34816
	ds_read_b128 v[204:207], v160 offset:35840
	ds_read_b128 v[208:211], v160 offset:36864
	ds_read_b128 v[212:215], v160 offset:37888
	ds_read_b128 v[216:219], v160 offset:38912
	ds_read_b128 v[220:223], v160 offset:39936
	global_load_lds_dwordx4 v[232:233], off
	v_lshl_add_u64 v[232:233], s[50:51], 0, v[132:133]
	s_mov_b32 m0, s60
	s_nop 0
	global_load_lds_dwordx4 v[232:233], off
	s_waitcnt vmcnt(8)
	s_waitcnt lgkmcnt(0)
	s_setprio 1
	s_barrier
	v_mfma_f32_16x16x32_bf16 v[64:67], v[150:153], v[192:195], v[64:67]
	v_mfma_f32_16x16x32_bf16 v[28:31], v[166:169], v[192:195], v[28:31]
	v_mfma_f32_16x16x32_bf16 v[60:63], v[150:153], v[200:203], v[60:63]
	v_mfma_f32_16x16x32_bf16 v[24:27], v[166:169], v[200:203], v[24:27]
	v_mfma_f32_16x16x32_bf16 v[56:59], v[150:153], v[208:211], v[56:59]
	v_mfma_f32_16x16x32_bf16 v[20:23], v[166:169], v[208:211], v[20:23]
	v_mfma_f32_16x16x32_bf16 v[52:55], v[150:153], v[216:219], v[52:55]
	v_mfma_f32_16x16x32_bf16 v[16:19], v[166:169], v[216:219], v[16:19]
	v_mfma_f32_16x16x32_bf16 v[64:67], v[162:165], v[196:199], v[64:67]
	v_mfma_f32_16x16x32_bf16 v[28:31], v[170:173], v[196:199], v[28:31]
	v_mfma_f32_16x16x32_bf16 v[60:63], v[162:165], v[204:207], v[60:63]
	v_mfma_f32_16x16x32_bf16 v[24:27], v[170:173], v[204:207], v[24:27]
	v_mfma_f32_16x16x32_bf16 v[56:59], v[162:165], v[212:215], v[56:59]
	v_mfma_f32_16x16x32_bf16 v[20:23], v[170:173], v[212:215], v[20:23]
	v_mfma_f32_16x16x32_bf16 v[52:55], v[162:165], v[220:223], v[52:55]
	v_mfma_f32_16x16x32_bf16 v[16:19], v[170:173], v[220:223], v[16:19]
	v_mfma_f32_16x16x32_bf16 v[124:127], v[174:177], v[192:195], v[124:127]
	v_mfma_f32_16x16x32_bf16 v[120:123], v[184:187], v[192:195], v[120:123]
	v_mfma_f32_16x16x32_bf16 v[116:119], v[174:177], v[200:203], v[116:119]
	v_mfma_f32_16x16x32_bf16 v[112:115], v[184:187], v[200:203], v[112:115]
	v_mfma_f32_16x16x32_bf16 v[108:111], v[174:177], v[208:211], v[108:111]
	v_mfma_f32_16x16x32_bf16 v[104:107], v[184:187], v[208:211], v[104:107]
	v_mfma_f32_16x16x32_bf16 v[100:103], v[174:177], v[216:219], v[100:103]
	v_mfma_f32_16x16x32_bf16 v[96:99], v[184:187], v[216:219], v[96:99]
	v_mfma_f32_16x16x32_bf16 v[124:127], v[178:181], v[196:199], v[124:127]
	v_mfma_f32_16x16x32_bf16 v[120:123], v[188:191], v[196:199], v[120:123]
	v_mfma_f32_16x16x32_bf16 v[116:119], v[178:181], v[204:207], v[116:119]
	v_mfma_f32_16x16x32_bf16 v[112:115], v[188:191], v[204:207], v[112:115]
	v_mfma_f32_16x16x32_bf16 v[108:111], v[178:181], v[212:215], v[108:111]
	v_mfma_f32_16x16x32_bf16 v[104:107], v[188:191], v[212:215], v[104:107]
	v_mfma_f32_16x16x32_bf16 v[100:103], v[178:181], v[220:223], v[100:103]
	v_mfma_f32_16x16x32_bf16 v[96:99], v[188:191], v[220:223], v[96:99]
	s_barrier
	s_setprio 0
	s_add_i32 s50, s78, s56
	v_lshl_add_u64 v[224:225], v[224:225], 0, s[28:29]
	s_mov_b32 m0, s50
	ds_read_b128 v[192:195], v160 offset:49152
	ds_read_b128 v[196:199], v160 offset:50176
	ds_read_b128 v[200:203], v160 offset:51200
	ds_read_b128 v[204:207], v160 offset:52224
	ds_read_b128 v[208:211], v160 offset:53248
	ds_read_b128 v[212:215], v160 offset:54272
	ds_read_b128 v[216:219], v160 offset:55296
	ds_read_b128 v[220:223], v160 offset:56320
	global_load_lds_dwordx4 v[224:225], off
	s_add_i32 m0, s50, 0x2000
	s_add_u32 s48, s48, 0x40080
	v_lshl_add_u64 v[224:225], v[226:227], 0, s[28:29]
	s_addc_u32 s49, s49, 0
	s_add_i32 s50, s79, s56
	global_load_lds_dwordx4 v[224:225], off
	v_lshl_add_u64 v[224:225], s[48:49], 0, v[130:131]
	s_mov_b32 m0, s50
	s_nop 0
	global_load_lds_dwordx4 v[224:225], off
	v_lshl_add_u64 v[224:225], s[48:49], 0, v[134:135]
	s_add_i32 m0, s50, 0x2000
	s_nop 0
	global_load_lds_dwordx4 v[224:225], off
	v_lshl_add_u64 v[224:225], v[228:229], 0, s[28:29]
	s_mov_b32 m0, s63
	s_nop 0
	global_load_lds_dwordx4 v[224:225], off
	v_lshl_add_u64 v[224:225], v[230:231], 0, s[28:29]
	s_mov_b32 m0, s64
	s_nop 0
	global_load_lds_dwordx4 v[224:225], off
	s_waitcnt vmcnt(8)
	s_waitcnt lgkmcnt(0)
	s_setprio 1
	s_barrier
	v_mfma_f32_16x16x32_bf16 v[44:47], v[150:153], v[192:195], v[44:47]
	v_mfma_f32_16x16x32_bf16 v[12:15], v[166:169], v[192:195], v[12:15]
	v_mfma_f32_16x16x32_bf16 v[40:43], v[150:153], v[200:203], v[40:43]
	v_mfma_f32_16x16x32_bf16 v[8:11], v[166:169], v[200:203], v[8:11]
	v_mfma_f32_16x16x32_bf16 v[36:39], v[150:153], v[208:211], v[36:39]
	v_mfma_f32_16x16x32_bf16 v[4:7], v[166:169], v[208:211], v[4:7]
	v_mfma_f32_16x16x32_bf16 v[32:35], v[150:153], v[216:219], v[32:35]
	v_mfma_f32_16x16x32_bf16 v[0:3], v[166:169], v[216:219], v[0:3]
	v_mfma_f32_16x16x32_bf16 v[44:47], v[162:165], v[196:199], v[44:47]
	v_mfma_f32_16x16x32_bf16 v[12:15], v[170:173], v[196:199], v[12:15]
	v_mfma_f32_16x16x32_bf16 v[40:43], v[162:165], v[204:207], v[40:43]
	v_mfma_f32_16x16x32_bf16 v[8:11], v[170:173], v[204:207], v[8:11]
	v_mfma_f32_16x16x32_bf16 v[36:39], v[162:165], v[212:215], v[36:39]
	v_mfma_f32_16x16x32_bf16 v[4:7], v[170:173], v[212:215], v[4:7]
	v_mfma_f32_16x16x32_bf16 v[32:35], v[162:165], v[220:223], v[32:35]
	v_mfma_f32_16x16x32_bf16 v[0:3], v[170:173], v[220:223], v[0:3]
	v_mfma_f32_16x16x32_bf16 v[92:95], v[174:177], v[192:195], v[92:95]
	v_mfma_f32_16x16x32_bf16 v[88:91], v[184:187], v[192:195], v[88:91]
	v_mfma_f32_16x16x32_bf16 v[84:87], v[174:177], v[200:203], v[84:87]
	v_mfma_f32_16x16x32_bf16 v[80:83], v[184:187], v[200:203], v[80:83]
	v_mfma_f32_16x16x32_bf16 v[76:79], v[174:177], v[208:211], v[76:79]
	v_mfma_f32_16x16x32_bf16 v[72:75], v[184:187], v[208:211], v[72:75]
	v_mfma_f32_16x16x32_bf16 v[68:71], v[174:177], v[216:219], v[68:71]
	v_mfma_f32_16x16x32_bf16 v[48:51], v[184:187], v[216:219], v[48:51]
	v_mfma_f32_16x16x32_bf16 v[92:95], v[178:181], v[196:199], v[92:95]
	v_mfma_f32_16x16x32_bf16 v[88:91], v[188:191], v[196:199], v[88:91]
	v_mfma_f32_16x16x32_bf16 v[84:87], v[178:181], v[204:207], v[84:87]
	v_mfma_f32_16x16x32_bf16 v[80:83], v[188:191], v[204:207], v[80:83]
	v_mfma_f32_16x16x32_bf16 v[76:79], v[178:181], v[212:215], v[76:79]
	v_mfma_f32_16x16x32_bf16 v[72:75], v[188:191], v[212:215], v[72:75]
	v_mfma_f32_16x16x32_bf16 v[68:71], v[178:181], v[220:223], v[68:71]
	v_mfma_f32_16x16x32_bf16 v[48:51], v[188:191], v[220:223], v[48:51]
	s_barrier
	s_setprio 0
	s_add_i32 s77, s77, 2
	s_add_u32 s46, s46, 0x100
	s_addc_u32 s47, s47, 0
	s_add_u32 s75, s75, 0x100
	s_addc_u32 s76, s76, 0
	s_cmp_gt_u32 s77, 13
	s_cbranch_scc0 .LBB0_475
	s_and_b64 vcc, exec, s[30:31]
	s_cbranch_vccnz .LBB0_479
	v_lshl_add_u32 v162, s44, 8, v155
	s_cmp_lg_u32 s0, 22
	s_mov_b64 s[44:45], -1
	s_cbranch_scc1 .LBB0_480

.LBB0_1274:
	ds_read_b128 v[150:153], v147
	ds_read_b128 v[154:157], v147 offset:1024
	ds_read_b128 v[158:161], v147 offset:2048
	ds_read_b128 v[162:165], v147 offset:3072
	ds_read_b128 v[166:169], v148
	ds_read_b128 v[170:173], v148 offset:1024
	ds_read_b128 v[174:177], v148 offset:2048
	ds_read_b128 v[178:181], v148 offset:3072
	s_add_u32 s28, s4, 0xffea0080
	s_addc_u32 s29, s5, -1
	s_cmp_eq_u32 s59, 28
	s_cselect_b32 s31, s25, s29
	s_cselect_b32 s30, s24, s28
	s_cselect_b32 s29, s23, s58
	s_cselect_b32 s28, s56, s57
	v_lshl_add_u64 v[216:217], s[4:5], 0, v[136:137]
	s_add_i32 m0, s39, 0xc000
	ds_read_b128 v[184:187], v149
	ds_read_b128 v[188:191], v149 offset:1024
	ds_read_b128 v[192:195], v149 offset:2048
	ds_read_b128 v[196:199], v149 offset:3072
	ds_read_b128 v[200:203], v149 offset:4096
	ds_read_b128 v[204:207], v149 offset:5120
	ds_read_b128 v[208:211], v149 offset:6144
	ds_read_b128 v[212:215], v149 offset:7168
	global_load_lds_dwordx4 v[216:217], off
	v_lshl_add_u64 v[216:217], s[4:5], 0, v[138:139]
	s_add_i32 m0, s39, 0xe000
	s_nop 0
	global_load_lds_dwordx4 v[216:217], off
	s_waitcnt vmcnt(8)
	s_waitcnt lgkmcnt(0)
	s_setprio 1
	s_barrier
	v_mfma_f32_16x16x32_bf16 v[124:127], v[150:153], v[184:187], v[124:127]
	v_mfma_f32_16x16x32_bf16 v[120:123], v[158:161], v[184:187], v[120:123]
	v_mfma_f32_16x16x32_bf16 v[116:119], v[150:153], v[192:195], v[116:119]
	v_mfma_f32_16x16x32_bf16 v[112:115], v[158:161], v[192:195], v[112:115]
	v_mfma_f32_16x16x32_bf16 v[100:103], v[150:153], v[200:203], v[100:103]
	v_mfma_f32_16x16x32_bf16 v[96:99], v[158:161], v[200:203], v[96:99]
	v_mfma_f32_16x16x32_bf16 v[84:87], v[150:153], v[208:211], v[84:87]
	v_mfma_f32_16x16x32_bf16 v[80:83], v[158:161], v[208:211], v[80:83]
	v_mfma_f32_16x16x32_bf16 v[124:127], v[154:157], v[188:191], v[124:127]
	v_mfma_f32_16x16x32_bf16 v[120:123], v[162:165], v[188:191], v[120:123]
	v_mfma_f32_16x16x32_bf16 v[116:119], v[154:157], v[196:199], v[116:119]
	v_mfma_f32_16x16x32_bf16 v[112:115], v[162:165], v[196:199], v[112:115]
	v_mfma_f32_16x16x32_bf16 v[100:103], v[154:157], v[204:207], v[100:103]
	v_mfma_f32_16x16x32_bf16 v[96:99], v[162:165], v[204:207], v[96:99]
	v_mfma_f32_16x16x32_bf16 v[84:87], v[154:157], v[212:215], v[84:87]
	v_mfma_f32_16x16x32_bf16 v[80:83], v[162:165], v[212:215], v[80:83]
	v_mfma_f32_16x16x32_bf16 v[108:111], v[166:169], v[184:187], v[108:111]
	v_mfma_f32_16x16x32_bf16 v[104:107], v[174:177], v[184:187], v[104:107]
	v_mfma_f32_16x16x32_bf16 v[92:95], v[166:169], v[192:195], v[92:95]
	v_mfma_f32_16x16x32_bf16 v[88:91], v[174:177], v[192:195], v[88:91]
	v_mfma_f32_16x16x32_bf16 v[76:79], v[166:169], v[200:203], v[76:79]
	v_mfma_f32_16x16x32_bf16 v[72:75], v[174:177], v[200:203], v[72:75]
	v_mfma_f32_16x16x32_bf16 v[68:71], v[166:169], v[208:211], v[68:71]
	v_mfma_f32_16x16x32_bf16 v[64:67], v[174:177], v[208:211], v[64:67]
	v_mfma_f32_16x16x32_bf16 v[108:111], v[170:173], v[188:191], v[108:111]
	v_mfma_f32_16x16x32_bf16 v[104:107], v[178:181], v[188:191], v[104:107]
	v_mfma_f32_16x16x32_bf16 v[92:95], v[170:173], v[196:199], v[92:95]
	v_mfma_f32_16x16x32_bf16 v[88:91], v[178:181], v[196:199], v[88:91]
	v_mfma_f32_16x16x32_bf16 v[76:79], v[170:173], v[204:207], v[76:79]
	v_mfma_f32_16x16x32_bf16 v[72:75], v[178:181], v[204:207], v[72:75]
	v_mfma_f32_16x16x32_bf16 v[68:71], v[170:173], v[212:215], v[68:71]
	v_mfma_f32_16x16x32_bf16 v[64:67], v[178:181], v[212:215], v[64:67]
	s_barrier
	s_setprio 0
	s_add_i32 s60, s47, s38
	v_lshl_add_u64 v[216:217], s[28:29], 0, v[130:131]
	s_mov_b32 m0, s60
	ds_read_b128 v[184:187], v149 offset:16384
	ds_read_b128 v[188:191], v149 offset:17408
	ds_read_b128 v[192:195], v149 offset:18432
	ds_read_b128 v[196:199], v149 offset:19456
	ds_read_b128 v[200:203], v149 offset:20480
	ds_read_b128 v[204:207], v149 offset:21504
	ds_read_b128 v[208:211], v149 offset:22528
	ds_read_b128 v[212:215], v149 offset:23552
	global_load_lds_dwordx4 v[216:217], off
	s_add_i32 m0, s60, 0x2000
	s_add_u32 s60, s28, 0x80000
	v_lshl_add_u64 v[218:219], s[28:29], 0, v[134:135]
	s_addc_u32 s61, s29, 0
	s_add_i32 s62, s48, s38
	global_load_lds_dwordx4 v[218:219], off
	v_lshl_add_u64 v[220:221], s[60:61], 0, v[130:131]
	s_mov_b32 m0, s62
	v_lshl_add_u64 v[222:223], s[30:31], 0, v[132:133]
	global_load_lds_dwordx4 v[220:221], off
	v_lshl_add_u64 v[220:221], s[60:61], 0, v[134:135]
	s_add_i32 m0, s62, 0x2000
	s_nop 0
	global_load_lds_dwordx4 v[220:221], off
	v_lshl_add_u64 v[220:221], s[30:31], 0, v[128:129]
	s_mov_b32 m0, s39
	s_nop 0
	global_load_lds_dwordx4 v[220:221], off
	s_mov_b32 m0, s40
	s_nop 0
	global_load_lds_dwordx4 v[222:223], off
	s_waitcnt vmcnt(8)
	s_waitcnt lgkmcnt(0)
	s_setprio 1
	s_barrier
	v_mfma_f32_16x16x32_bf16 v[60:63], v[150:153], v[184:187], v[60:63]
	v_mfma_f32_16x16x32_bf16 v[56:59], v[158:161], v[184:187], v[56:59]
	v_mfma_f32_16x16x32_bf16 v[52:55], v[150:153], v[192:195], v[52:55]
	v_mfma_f32_16x16x32_bf16 v[48:51], v[158:161], v[192:195], v[48:51]
	v_mfma_f32_16x16x32_bf16 v[36:39], v[150:153], v[200:203], v[36:39]
	v_mfma_f32_16x16x32_bf16 v[32:35], v[158:161], v[200:203], v[32:35]
	v_mfma_f32_16x16x32_bf16 v[20:23], v[150:153], v[208:211], v[20:23]
	v_mfma_f32_16x16x32_bf16 v[16:19], v[158:161], v[208:211], v[16:19]
	v_mfma_f32_16x16x32_bf16 v[60:63], v[154:157], v[188:191], v[60:63]
	v_mfma_f32_16x16x32_bf16 v[56:59], v[162:165], v[188:191], v[56:59]
	v_mfma_f32_16x16x32_bf16 v[52:55], v[154:157], v[196:199], v[52:55]
	v_mfma_f32_16x16x32_bf16 v[48:51], v[162:165], v[196:199], v[48:51]
	v_mfma_f32_16x16x32_bf16 v[36:39], v[154:157], v[204:207], v[36:39]
	v_mfma_f32_16x16x32_bf16 v[32:35], v[162:165], v[204:207], v[32:35]
	v_mfma_f32_16x16x32_bf16 v[20:23], v[154:157], v[212:215], v[20:23]
	v_mfma_f32_16x16x32_bf16 v[16:19], v[162:165], v[212:215], v[16:19]
	v_mfma_f32_16x16x32_bf16 v[44:47], v[166:169], v[184:187], v[44:47]
	v_mfma_f32_16x16x32_bf16 v[40:43], v[174:177], v[184:187], v[40:43]
	v_mfma_f32_16x16x32_bf16 v[28:31], v[166:169], v[192:195], v[28:31]
	v_mfma_f32_16x16x32_bf16 v[24:27], v[174:177], v[192:195], v[24:27]
	v_mfma_f32_16x16x32_bf16 v[12:15], v[166:169], v[200:203], v[12:15]
	v_mfma_f32_16x16x32_bf16 v[8:11], v[174:177], v[200:203], v[8:11]
	v_mfma_f32_16x16x32_bf16 v[4:7], v[166:169], v[208:211], v[4:7]
	v_mfma_f32_16x16x32_bf16 v[0:3], v[174:177], v[208:211], v[0:3]
	v_mfma_f32_16x16x32_bf16 v[44:47], v[170:173], v[188:191], v[44:47]
	v_mfma_f32_16x16x32_bf16 v[40:43], v[178:181], v[188:191], v[40:43]
	v_mfma_f32_16x16x32_bf16 v[28:31], v[170:173], v[196:199], v[28:31]
	v_mfma_f32_16x16x32_bf16 v[24:27], v[178:181], v[196:199], v[24:27]
	v_mfma_f32_16x16x32_bf16 v[12:15], v[170:173], v[204:207], v[12:15]
	v_mfma_f32_16x16x32_bf16 v[8:11], v[178:181], v[204:207], v[8:11]
	v_mfma_f32_16x16x32_bf16 v[4:7], v[170:173], v[212:215], v[4:7]
	v_mfma_f32_16x16x32_bf16 v[0:3], v[178:181], v[212:215], v[0:3]
	s_barrier
	s_setprio 0
	s_add_i32 s60, 0, 0x18000
	s_add_i32 s61, 0, 0x1c000
	v_add_u32_e32 v162, s60, v145
	v_add_u32_e32 v178, s61, v145
	ds_read_b128 v[150:153], v162
	ds_read_b128 v[154:157], v162 offset:1024
	ds_read_b128 v[158:161], v162 offset:2048
	ds_read_b128 v[162:165], v162 offset:3072
	ds_read_b128 v[166:169], v178
	ds_read_b128 v[170:173], v178 offset:1024
	ds_read_b128 v[174:177], v178 offset:2048
	ds_read_b128 v[178:181], v178 offset:3072
	s_add_u32 s30, s30, 0x160000
	s_addc_u32 s31, s31, 0
	s_mov_b32 m0, s41
	v_lshl_add_u64 v[224:225], s[30:31], 0, v[128:129]
	ds_read_b128 v[184:187], v149 offset:32768
	ds_read_b128 v[188:191], v149 offset:33792
	ds_read_b128 v[192:195], v149 offset:34816
	ds_read_b128 v[196:199], v149 offset:35840
	ds_read_b128 v[200:203], v149 offset:36864
	ds_read_b128 v[204:207], v149 offset:37888
	ds_read_b128 v[208:211], v149 offset:38912
	ds_read_b128 v[212:215], v149 offset:39936
	global_load_lds_dwordx4 v[224:225], off
	v_lshl_add_u64 v[224:225], s[30:31], 0, v[132:133]
	s_mov_b32 m0, s42
	s_nop 0
	global_load_lds_dwordx4 v[224:225], off
	s_waitcnt vmcnt(8)
	s_waitcnt lgkmcnt(0)
	s_setprio 1
	s_barrier
	v_mfma_f32_16x16x32_bf16 v[124:127], v[150:153], v[184:187], v[124:127]
	v_mfma_f32_16x16x32_bf16 v[120:123], v[158:161], v[184:187], v[120:123]
	v_mfma_f32_16x16x32_bf16 v[116:119], v[150:153], v[192:195], v[116:119]
	v_mfma_f32_16x16x32_bf16 v[112:115], v[158:161], v[192:195], v[112:115]
	v_mfma_f32_16x16x32_bf16 v[100:103], v[150:153], v[200:203], v[100:103]
	v_mfma_f32_16x16x32_bf16 v[96:99], v[158:161], v[200:203], v[96:99]
	v_mfma_f32_16x16x32_bf16 v[84:87], v[150:153], v[208:211], v[84:87]
	v_mfma_f32_16x16x32_bf16 v[80:83], v[158:161], v[208:211], v[80:83]
	v_mfma_f32_16x16x32_bf16 v[124:127], v[154:157], v[188:191], v[124:127]
	v_mfma_f32_16x16x32_bf16 v[120:123], v[162:165], v[188:191], v[120:123]
	v_mfma_f32_16x16x32_bf16 v[116:119], v[154:157], v[196:199], v[116:119]
	v_mfma_f32_16x16x32_bf16 v[112:115], v[162:165], v[196:199], v[112:115]
	v_mfma_f32_16x16x32_bf16 v[100:103], v[154:157], v[204:207], v[100:103]
	v_mfma_f32_16x16x32_bf16 v[96:99], v[162:165], v[204:207], v[96:99]
	v_mfma_f32_16x16x32_bf16 v[84:87], v[154:157], v[212:215], v[84:87]
	v_mfma_f32_16x16x32_bf16 v[80:83], v[162:165], v[212:215], v[80:83]
	v_mfma_f32_16x16x32_bf16 v[108:111], v[166:169], v[184:187], v[108:111]
	v_mfma_f32_16x16x32_bf16 v[104:107], v[174:177], v[184:187], v[104:107]
	v_mfma_f32_16x16x32_bf16 v[92:95], v[166:169], v[192:195], v[92:95]
	v_mfma_f32_16x16x32_bf16 v[88:91], v[174:177], v[192:195], v[88:91]
	v_mfma_f32_16x16x32_bf16 v[76:79], v[166:169], v[200:203], v[76:79]
	v_mfma_f32_16x16x32_bf16 v[72:75], v[174:177], v[200:203], v[72:75]
	v_mfma_f32_16x16x32_bf16 v[68:71], v[166:169], v[208:211], v[68:71]
	v_mfma_f32_16x16x32_bf16 v[64:67], v[174:177], v[208:211], v[64:67]
	v_mfma_f32_16x16x32_bf16 v[108:111], v[170:173], v[188:191], v[108:111]
	v_mfma_f32_16x16x32_bf16 v[104:107], v[178:181], v[188:191], v[104:107]
	v_mfma_f32_16x16x32_bf16 v[92:95], v[170:173], v[196:199], v[92:95]
	v_mfma_f32_16x16x32_bf16 v[88:91], v[178:181], v[196:199], v[88:91]
	v_mfma_f32_16x16x32_bf16 v[76:79], v[170:173], v[204:207], v[76:79]
	v_mfma_f32_16x16x32_bf16 v[72:75], v[178:181], v[204:207], v[72:75]
	v_mfma_f32_16x16x32_bf16 v[68:71], v[170:173], v[212:215], v[68:71]
	v_mfma_f32_16x16x32_bf16 v[64:67], v[178:181], v[212:215], v[64:67]
	s_barrier
	s_setprio 0
	s_add_i32 s30, s60, s38
	v_lshl_add_u64 v[216:217], v[216:217], 0, s[10:11]
	s_mov_b32 m0, s30
	ds_read_b128 v[184:187], v149 offset:49152
	ds_read_b128 v[188:191], v149 offset:50176
	ds_read_b128 v[192:195], v149 offset:51200
	ds_read_b128 v[196:199], v149 offset:52224
	ds_read_b128 v[200:203], v149 offset:53248
	ds_read_b128 v[204:207], v149 offset:54272
	ds_read_b128 v[208:211], v149 offset:55296
	ds_read_b128 v[212:215], v149 offset:56320
	global_load_lds_dwordx4 v[216:217], off
	s_add_i32 m0, s30, 0x2000
	s_add_u32 s28, s28, 0x80080
	v_lshl_add_u64 v[216:217], v[218:219], 0, s[10:11]
	s_addc_u32 s29, s29, 0
	s_add_i32 s30, s61, s38
	global_load_lds_dwordx4 v[216:217], off
	v_lshl_add_u64 v[216:217], s[28:29], 0, v[130:131]
	s_mov_b32 m0, s30
	s_nop 0
	global_load_lds_dwordx4 v[216:217], off
	v_lshl_add_u64 v[216:217], s[28:29], 0, v[134:135]
	s_add_i32 m0, s30, 0x2000
	s_nop 0
	global_load_lds_dwordx4 v[216:217], off
	v_lshl_add_u64 v[216:217], v[220:221], 0, s[10:11]
	s_mov_b32 m0, s45
	s_nop 0
	global_load_lds_dwordx4 v[216:217], off
	v_lshl_add_u64 v[216:217], v[222:223], 0, s[10:11]
	s_mov_b32 m0, s46
	s_nop 0
	global_load_lds_dwordx4 v[216:217], off
	s_waitcnt vmcnt(8)
	s_waitcnt lgkmcnt(0)
	s_setprio 1
	s_barrier
	v_mfma_f32_16x16x32_bf16 v[60:63], v[150:153], v[184:187], v[60:63]
	v_mfma_f32_16x16x32_bf16 v[56:59], v[158:161], v[184:187], v[56:59]
	v_mfma_f32_16x16x32_bf16 v[52:55], v[150:153], v[192:195], v[52:55]
	v_mfma_f32_16x16x32_bf16 v[48:51], v[158:161], v[192:195], v[48:51]
	v_mfma_f32_16x16x32_bf16 v[36:39], v[150:153], v[200:203], v[36:39]
	v_mfma_f32_16x16x32_bf16 v[32:35], v[158:161], v[200:203], v[32:35]
	v_mfma_f32_16x16x32_bf16 v[20:23], v[150:153], v[208:211], v[20:23]
	v_mfma_f32_16x16x32_bf16 v[16:19], v[158:161], v[208:211], v[16:19]
	v_mfma_f32_16x16x32_bf16 v[60:63], v[154:157], v[188:191], v[60:63]
	v_mfma_f32_16x16x32_bf16 v[56:59], v[162:165], v[188:191], v[56:59]
	v_mfma_f32_16x16x32_bf16 v[52:55], v[154:157], v[196:199], v[52:55]
	v_mfma_f32_16x16x32_bf16 v[48:51], v[162:165], v[196:199], v[48:51]
	v_mfma_f32_16x16x32_bf16 v[36:39], v[154:157], v[204:207], v[36:39]
	v_mfma_f32_16x16x32_bf16 v[32:35], v[162:165], v[204:207], v[32:35]
	v_mfma_f32_16x16x32_bf16 v[20:23], v[154:157], v[212:215], v[20:23]
	v_mfma_f32_16x16x32_bf16 v[16:19], v[162:165], v[212:215], v[16:19]
	v_mfma_f32_16x16x32_bf16 v[44:47], v[166:169], v[184:187], v[44:47]
	v_mfma_f32_16x16x32_bf16 v[40:43], v[174:177], v[184:187], v[40:43]
	v_mfma_f32_16x16x32_bf16 v[28:31], v[166:169], v[192:195], v[28:31]
	v_mfma_f32_16x16x32_bf16 v[24:27], v[174:177], v[192:195], v[24:27]
	v_mfma_f32_16x16x32_bf16 v[12:15], v[166:169], v[200:203], v[12:15]
	v_mfma_f32_16x16x32_bf16 v[8:11], v[174:177], v[200:203], v[8:11]
	v_mfma_f32_16x16x32_bf16 v[4:7], v[166:169], v[208:211], v[4:7]
	v_mfma_f32_16x16x32_bf16 v[0:3], v[174:177], v[208:211], v[0:3]
	v_mfma_f32_16x16x32_bf16 v[44:47], v[170:173], v[188:191], v[44:47]
	v_mfma_f32_16x16x32_bf16 v[40:43], v[178:181], v[188:191], v[40:43]
	v_mfma_f32_16x16x32_bf16 v[28:31], v[170:173], v[196:199], v[28:31]
	v_mfma_f32_16x16x32_bf16 v[24:27], v[178:181], v[196:199], v[24:27]
	v_mfma_f32_16x16x32_bf16 v[12:15], v[170:173], v[204:207], v[12:15]
	v_mfma_f32_16x16x32_bf16 v[8:11], v[178:181], v[204:207], v[8:11]
	v_mfma_f32_16x16x32_bf16 v[4:7], v[170:173], v[212:215], v[4:7]
	v_mfma_f32_16x16x32_bf16 v[0:3], v[178:181], v[212:215], v[0:3]
	s_barrier
	s_setprio 0
	s_add_i32 s59, s59, 2
	s_add_u32 s4, s4, 0x100
	s_addc_u32 s5, s5, 0
	s_add_u32 s57, s57, 0x100
	s_addc_u32 s58, s58, 0
	s_cmp_gt_u32 s59, 29
	s_cbranch_scc0 .LBB0_1274
	s_and_b64 vcc, exec, s[12:13]
	s_cbranch_vccz .LBB0_1277
	s_barrier
